# v50 with the memory-norm row stride derived from the grid size
# speedup vs baseline: 1.0035x; 1.0001x over previous
; DI unsigned cvt_pk_bf16(float lo, float hi) { const f32x2 v = {lo, hi}; return __builtin_bit_cast(unsigned, __builtin_convertvector(v, bf16x2_t)); }
; template <bool XIN_BF, bool XOUT_BF>
; DI void norm_row(const void* xin, const bf16_t* Rrow, const float* gpost, void* xout, const float* gpre, bf16_t* xn, int lane) {
;     ...
;     if (xn) {
;         float ss = 0.f;
; #pragma unroll
;         for (int j = 0; j < 4; ++j) ss += (v[j][0] * v[j][0] + v[j][1] * v[j][1]) + (v[j][2] * v[j][2] + v[j][3] * v[j][3]);
;         const float rinv = __builtin_amdgcn_rsqf(wave_sum(ss) * (1.f / 1024.f) + EPS);
; #pragma unroll
;         for (int j = 0; j < 4; ++j) { const f32x4 g = *(const f32x4*)(gpre + 4 * lane + 256 * j); const f32x4 o = v[j] * rinv * g;
;             u32x2 w; w.x = cvt_pk_bf16(o[0], o[1]); w.y = cvt_pk_bf16(o[2], o[3]); *(u32x2*)(xn + 4 * lane + 256 * j) = w; }
; __global__ void __launch_bounds__(512, 2) mega(Args args) {
;     ...
;                 if (half == 0) for (int m = gw; m < 3072; m += NGW) { const float* mi = m < 1024 ? in.mem_prompt + (size_t)m * D : in.mem_sample + (size_t)(m - 1024) * D;
;                     norm_row<false, true>(mi, nullptr, nullptr, nullptr, in.g_mem + l * D, MNb + (size_t)m * D, lane); }
.LBB0_371:
	s_and_b64 s[2:3], s[90:91], exec
	s_cbranch_scc0 .Lmn_skip
	v_readlane_b32 s2, v255, 8
	s_cmpk_lt_u32 s2, 0x80
	s_cbranch_scc1 .Lmn_skip
	v_readlane_b32 s3, v255, 3
	v_readlane_b32 s6, v255, 9
	v_readlane_b32 s7, v255, 10
	s_addk_i32 s2, 0xff80
	s_lshl_b32 s2, s2, 3
	s_add_i32 s24, s2, s3
	v_readlane_b32 s16, v255, 11
	s_addk_i32 s16, 0xff80
	s_lshl_b32 s16, s16, 3
	s_load_dwordx2 s[14:15], s[6:7], 0xa8
	s_load_dwordx2 s[10:11], s[6:7], 0xe8
	s_load_dwordx4 s[4:7], s[6:7], 0x10
	v_lshlrev_b32_e32 v0, 4, v249
	v_lshlrev_b32_e32 v1, 3, v249
	v_readlane_b32 s12, v255, 15
	s_lshl_b32 s12, s12, 2
	s_waitcnt lgkmcnt(0)
	s_add_u32 s14, s14, s12
	s_addc_u32 s15, s15, 0
	s_add_u32 s10, s10, 0x4000000
	s_addc_u32 s11, s11, 0
	global_load_dwordx4 v[20:23], v0, s[14:15]
	global_load_dwordx4 v[24:27], v0, s[14:15] offset:1024
	global_load_dwordx4 v[28:31], v0, s[14:15] offset:2048
	global_load_dwordx4 v[32:35], v0, s[14:15] offset:3072
.Lmn_loop:
	s_add_i32 s25, s24, 0xfffffc00
	s_cmpk_lt_i32 s24, 0x400
	s_cselect_b32 s25, s24, s25
	s_cselect_b32 s12, s4, s6
	s_cselect_b32 s13, s5, s7
	s_lshl_b32 s25, s25, 12
	s_add_u32 s12, s12, s25
	s_addc_u32 s13, s13, 0
	global_load_dwordx4 v[4:7], v0, s[12:13]
	global_load_dwordx4 v[8:11], v0, s[12:13] offset:1024
	global_load_dwordx4 v[12:15], v0, s[12:13] offset:2048
	global_load_dwordx4 v[16:19], v0, s[12:13] offset:3072
	s_lshl_b32 s25, s24, 11
	s_add_u32 s12, s10, s25
	s_addc_u32 s13, s11, 0
	s_waitcnt vmcnt(0)
	v_mul_f32_e32 v37, v4, v4
	v_fmac_f32_e32 v37, v5, v5
	v_mul_f32_e32 v38, v6, v6
	v_fmac_f32_e32 v38, v7, v7
	v_add_f32_e32 v36, v37, v38
	v_mul_f32_e32 v37, v8, v8
	v_fmac_f32_e32 v37, v9, v9
	v_mul_f32_e32 v38, v10, v10
	v_fmac_f32_e32 v38, v11, v11
	v_add_f32_e32 v37, v37, v38
	v_add_f32_e32 v36, v36, v37
	v_mul_f32_e32 v37, v12, v12
	v_fmac_f32_e32 v37, v13, v13
	v_mul_f32_e32 v38, v14, v14
	v_fmac_f32_e32 v38, v15, v15
	v_add_f32_e32 v37, v37, v38
	v_add_f32_e32 v36, v36, v37
	v_mul_f32_e32 v37, v16, v16
	v_fmac_f32_e32 v37, v17, v17
	v_mul_f32_e32 v38, v18, v18
	v_fmac_f32_e32 v38, v19, v19
	v_add_f32_e32 v37, v37, v38
	v_add_f32_e32 v36, v36, v37
	ds_bpermute_b32 v37, v206, v36
	s_waitcnt lgkmcnt(0)
	v_add_f32_e32 v36, v36, v37
	ds_bpermute_b32 v37, v207, v36
	s_waitcnt lgkmcnt(0)
	v_add_f32_e32 v36, v36, v37
	ds_bpermute_b32 v37, v208, v36
	s_waitcnt lgkmcnt(0)
	v_add_f32_e32 v36, v36, v37
	ds_bpermute_b32 v37, v209, v36
	s_waitcnt lgkmcnt(0)
	v_add_f32_e32 v36, v36, v37
	ds_bpermute_b32 v37, v210, v36
	s_waitcnt lgkmcnt(0)
	v_add_f32_e32 v36, v36, v37
	ds_bpermute_b32 v37, v211, v36
	s_waitcnt lgkmcnt(0)
	v_add_f32_e32 v36, v36, v37
	v_fmamk_f32 v36, v36, 0x3a800000, v217
	v_rsq_f32_e32 v37, v36
	s_nop 0
	v_mul_f32_e32 v4, v4, v37
	v_mul_f32_e32 v5, v5, v37
	v_mul_f32_e32 v6, v6, v37
	v_mul_f32_e32 v7, v7, v37
	v_mul_f32_e32 v4, v4, v20
	v_mul_f32_e32 v5, v5, v21
	v_mul_f32_e32 v6, v6, v22
	v_mul_f32_e32 v7, v7, v23
	v_cvt_pk_bf16_f32 v4, v4, v5
	v_cvt_pk_bf16_f32 v5, v6, v7
	global_store_dwordx2 v1, v[4:5], s[12:13]
	v_mul_f32_e32 v8, v8, v37
	v_mul_f32_e32 v9, v9, v37
	v_mul_f32_e32 v10, v10, v37
	v_mul_f32_e32 v11, v11, v37
	v_mul_f32_e32 v8, v8, v24
	v_mul_f32_e32 v9, v9, v25
	v_mul_f32_e32 v10, v10, v26
	v_mul_f32_e32 v11, v11, v27
	v_cvt_pk_bf16_f32 v8, v8, v9
	v_cvt_pk_bf16_f32 v9, v10, v11
	global_store_dwordx2 v1, v[8:9], s[12:13] offset:512
	v_mul_f32_e32 v12, v12, v37
	v_mul_f32_e32 v13, v13, v37
	v_mul_f32_e32 v14, v14, v37
	v_mul_f32_e32 v15, v15, v37
	v_mul_f32_e32 v12, v12, v28
	v_mul_f32_e32 v13, v13, v29
	v_mul_f32_e32 v14, v14, v30
	v_mul_f32_e32 v15, v15, v31
	v_cvt_pk_bf16_f32 v12, v12, v13
	v_cvt_pk_bf16_f32 v13, v14, v15
	global_store_dwordx2 v1, v[12:13], s[12:13] offset:1024
	v_mul_f32_e32 v16, v16, v37
	v_mul_f32_e32 v17, v17, v37
	v_mul_f32_e32 v18, v18, v37
	v_mul_f32_e32 v19, v19, v37
	v_mul_f32_e32 v16, v16, v32
	v_mul_f32_e32 v17, v17, v33
	v_mul_f32_e32 v18, v18, v34
	v_mul_f32_e32 v19, v19, v35
	v_cvt_pk_bf16_f32 v16, v16, v17
	v_cvt_pk_bf16_f32 v17, v18, v19
	global_store_dwordx2 v1, v[16:17], s[12:13] offset:1536
	s_add_i32 s24, s24, s16
	s_cmpk_lt_i32 s24, 0xc00
	s_cbranch_scc1 .Lmn_loop
